# layer-1 mixer-A units dealt after the M2 queue runs dry (fills M2 idle), stacked on S3 waits + index loop/threshold exit + attn mask prefetch
# speedup vs baseline: 1.0210x; 1.0137x over previous
; #define LAS __attribute__((address_space(3)))
; __device__ __forceinline__ unsigned xb_add(unsigned* p, unsigned v) { return __hip_atomic_fetch_add(p, v, __ATOMIC_RELAXED, __HIP_MEMORY_SCOPE_AGENT); }
; __device__ __forceinline__ unsigned xb_xcc_id() { return (unsigned)__builtin_amdgcn_s_getreg((3 << 11) | 20) & 0xFu; }
; #define CAS __attribute__((address_space(4)))
;     __device__ __forceinline__ unsigned* ctl() const { return (unsigned*)(pp->ws + WS_CTL); }
; #define RETID() do { int _l; asm volatile("v_mbcnt_lo_u32_b32 %0, -1, 0\n\tv_mbcnt_hi_u32_b32 %0, -1, %0" : "=v"(_l)); c.lane = _l; c.tid = c.wave * 64 + _l; } while (0)
; __device__ __forceinline__ XcdBarrier xcd_barrier_post(unsigned* bar, volatile LAS unsigned* st, const bool t0  ) {
;     XcdBarrier b; b.bar = bar; b.x = xb_xcc_id(); b.st = st;
;     if (t0) (void)xb_add(&bar[XB_XCNT(b.x)], 1u);
;     return b;
; __global__ void __launch_bounds__(512, 2) hybrid_fwd(Params P) {
;     ...
;         c.pp = (const CAS Params*)__builtin_amdgcn_kernarg_segment_ptr();
;     c.lds = (LAS unsigned char*)lds_raw;
;     c.wave = __builtin_amdgcn_readfirstlane((int)(threadIdx.x >> 6));
;     ...
;     RETID();
;     if (c.tid < 32) ((LAS unsigned*)(c.lds + LDS_CTL))[c.tid] = 0u;
;     __syncthreads();
;     const int lo = P.ph_lo, hi = P.ph_hi;
;     XcdBarrier bar; bar.bar = c.ctl() + CW_BAR; bar.x = 0; bar.st = (volatile LAS unsigned*)(c.lds + LDS_CTL);
;     if (hi > lo) bar = xcd_barrier_post(c.ctl() + CW_BAR, (volatile LAS unsigned*)(c.lds + LDS_CTL), c.tid == 0);
_Z10hybrid_fwd6Params:
	v_writelane_b32 v255, 0, 62
	v_readfirstlane_b32 s4, v0
	v_writelane_b32 v250, s0, 0
	s_and_b32 s33, s4, 0xffffffc0
	v_mbcnt_lo_u32_b32 v0, -1, 0
	v_mbcnt_hi_u32_b32 v0, -1, v0
	s_mov_b32 s39, s2
	v_writelane_b32 v250, s1, 1
	s_load_dwordx2 s[0:1], s[0:1], 0xc8
	v_add_u32_e32 v173, s33, v0
	v_cmp_gt_i32_e32 vcc, 32, v173
	s_waitcnt lgkmcnt(0)
	v_writelane_b32 v250, s0, 2
	s_nop 1
	v_writelane_b32 v250, s1, 3
	s_and_saveexec_b64 s[0:1], vcc
	v_lshl_add_u32 v0, v173, 2, 0
	v_add_u32_e32 v0, 0x27f00, v0
	v_mov_b32_e32 v1, 0
	ds_write_b32 v0, v1
	s_or_b64 exec, exec, s[0:1]
	v_readlane_b32 s0, v250, 0
	v_readlane_b32 s1, v250, 1
	s_waitcnt lgkmcnt(0)
	s_barrier
	s_load_dwordx2 s[0:1], s[0:1], 0xc0
	s_waitcnt lgkmcnt(0)
	v_writelane_b32 v250, s0, 4
	s_nop 1
	v_writelane_b32 v250, s1, 5
	s_nop 0
	v_readlane_b32 s0, v250, 2
	v_readlane_b32 s1, v250, 3
	s_cmp_le_i32 s1, s0
	s_mov_b32 s0, 0
	v_writelane_b32 v250, s0, 6
	s_cbranch_scc1 .LBB0_7
	s_getreg_b32 s0, hwreg(HW_REG_XCC_ID, 0, 4)
	s_and_b32 s0, s0, 15
	v_cmp_eq_u32_e32 vcc, 0, v173
	v_writelane_b32 v250, s0, 6
	s_and_saveexec_b64 s[0:1], vcc
	s_cbranch_execz .LBB0_6
	s_mov_b64 s[2:3], exec
	v_mbcnt_lo_u32_b32 v0, s2, 0
	v_mbcnt_hi_u32_b32 v0, s3, v0
	v_cmp_eq_u32_e32 vcc, 0, v0
	s_and_b64 s[6:7], exec, vcc
	s_mov_b64 exec, s[6:7]
	s_cbranch_execz .LBB0_6
	v_readlane_b32 s5, v250, 6
	s_lshl_b32 s5, s5, 8
	v_readlane_b32 s6, v250, 4
	v_readlane_b32 s7, v250, 5
	s_add_u32 s6, s6, s5
	s_addc_u32 s7, s7, 0
	s_bcnt1_i32_b64 s2, s[2:3]
	v_mov_b32_e32 v0, 0x4000
	v_mov_b32_e32 v1, s2
	global_atomic_add v0, v1, s[6:7] offset:1024

; #define RETID() do { int _l; asm volatile("v_mbcnt_lo_u32_b32 %0, -1, 0\n\tv_mbcnt_hi_u32_b32 %0, -1, %0" : "=v"(_l)); c.lane = _l; c.tid = c.wave * 64 + _l; } while (0)
; __global__ void __launch_bounds__(512, 2) hybrid_fwd(Params P) {
;     ...
;     RETID();
.LBB0_2552:
	v_readlane_b32 s2, v250, 2
	v_readlane_b32 s3, v250, 3
	s_cmp_lt_i32 s2, 9
	s_cselect_b64 s[2:3], -1, 0
	s_and_b64 s[2:3], s[2:3], s[0:1]
	s_andn2_b64 vcc, exec, s[2:3]
	s_lshl_b32 s26, s28, 6
	v_mbcnt_lo_u32_b32 v0, -1, 0
	v_mbcnt_hi_u32_b32 v0, -1, v0
	s_cbranch_vccnz .LBB0_2809
; #define LAS __attribute__((address_space(3)))
; __device__ __forceinline__ void mixA_unit(const Ctx& c, int l, int a) {
;     const int b = a >> 7, chunk = (a >> 3) & 15, hh = a & 7, r0 = b * 2048 + chunk * 128;
;     LAS unsigned char* WmB = opq(c.lds);
;     LAS unsigned char* vT = opq(c.lds + 36864);
;     LAS float* mixed = opq((LAS float*)(c.lds + 73728));
;     LAS float* st_mean = opq((LAS float*)(c.lds + 73728 + 67584));
;     LAS float* st_rstd = st_mean + 128;
;     const bf16* VA = c.w<bf16>(WS_VA) + (size_t)r0 * 1024; const bf16* UA = c.w<bf16>(WS_UA) + (size_t)r0 * 1024; const bf16* ZA = c.w<bf16>(WS_ZA) + (size_t)r0 * 1024;
;     const int lane = c.lane, wave = c.wave, m = lane & 15, quad = lane >> 4;
; #pragma unroll
;     for (int half = 0; half < 2; ++half) {
;         u32x4 raw[8][2];
; #pragma unroll
;         for (int i = 0; i < 8; ++i) { const bf16* row = VA + (size_t)(wave * 16 + half * 8 + i) * 1024; raw[i][0] = *(const u32x4*)(row + lane * 8); raw[i][1] = *(const u32x4*)(row + 512 + lane * 8); }
; __device__ __forceinline__ void dprep_unit(const Ctx& c, int l, int b, int chunk, int h) {
;     LAS unsigned char* qs = opq(c.lds);
;     LAS unsigned char* ks = opq(c.lds + 18432);
;     LAS float* rhs = opq((LAS float*)(c.lds + 36864));
;     LAS float* a_s = opq((LAS float*)(c.lds + 102400));
;     LAS unsigned char* kgT = opq(c.lds + 118784);
;     LAS float* Gs = opq((LAS float*)(c.lds + 139264));
;     LAS float* betas = Gs + 64;
;     unsigned char* rec = c.ws() + WS_REC + (size_t)((b * 16 + h) * 32 + chunk) * REC_BYTES;
;     const int lane = c.lane, wave = c.wave, m = lane & 15, quad = lane >> 4;
;     const int row0 = b * 2048 + chunk * 64;
;     const bf16* base = c.w<bf16>(WS_QKVB) + (size_t)(b * 2048) * 6144 + h * 128 + 2 * lane;
;     const int t0 = chunk * 64 + 8 * wave;
;     unsigned xq[11], xk[11], xv[11];
; #pragma unroll
;     for (int jr = 0; jr < 11; ++jr) {
;         const int p = t0 - 3 + jr;
;         if (p >= 0) { const bf16* rp = base + (size_t)p * 6144; xq[jr] = *(const unsigned*)rp; xk[jr] = *(const unsigned*)(rp + 2048); xv[jr] = *(const unsigned*)(rp + 4096); }
;         else { xq[jr] = 0u; xk[jr] = 0u; xv[jr] = 0u; }
;     }
;     float wq[4][2], wk[4][2], wv[4][2];
;     const float* cw = c.f(I_CONVW) + (size_t)l * 4 * 6144 + h * 128 + 2 * lane;
; #pragma unroll
	s_lshl_b32 s8, s28, 4
	v_writelane_b32 v250, s2, 42
	s_ashr_i32 s9, s8, 31
	s_lshl_b64 s[0:1], s[8:9], 11
	v_writelane_b32 v250, s3, 43
	v_writelane_b32 v250, s0, 44
	s_mul_i32 s27, s28, 3
	v_readlane_b32 vcc_lo, v255, 62
	s_nop 3
	v_mov_b32_e32 v222, vcc_lo
	v_lshlrev_b32_e32 v222, 12, v222
	v_add_u32_e32 v222, 0x10000, v222
	v_writelane_b32 v250, s1, 45
	s_or_b32 s0, s8, 1
	s_ashr_i32 s1, s0, 31
	s_lshl_b64 s[0:1], s[0:1], 11
	v_writelane_b32 v250, s0, 46
	s_mov_b32 s35, 0x12000
	v_mov_b32_e32 v17, 0
	v_writelane_b32 v250, s1, 47
	s_or_b32 s0, s8, 2
	s_ashr_i32 s1, s0, 31
	s_lshl_b64 s[0:1], s[0:1], 11
	v_writelane_b32 v250, s0, 48
	v_mov_b32_e32 v223, 0x3ecc95a3
	v_mov_b32_e32 v224, 0x16000
	v_writelane_b32 v250, s1, 49
	s_or_b32 s0, s8, 3
	s_ashr_i32 s1, s0, 31
	s_lshl_b64 s[0:1], s[0:1], 11
	v_writelane_b32 v250, s0, 50
	v_mov_b32_e32 v225, 0x358637bd
	v_mov_b32_e32 v226, 0x3000
	v_writelane_b32 v250, s1, 51
	s_or_b32 s0, s8, 4
	s_ashr_i32 s1, s0, 31
	s_lshl_b64 s[0:1], s[0:1], 11
	v_writelane_b32 v250, s0, 52
	v_mov_b32_e32 v138, 0x7f800000
	v_mov_b32_e32 v228, 0x3f317218
	v_writelane_b32 v250, s1, 53
	s_or_b32 s0, s8, 5
	s_ashr_i32 s1, s0, 31
	s_lshl_b64 s[0:1], s[0:1], 11
	v_writelane_b32 v250, s0, 54
	v_mov_b32_e32 v139, 0xff800000
	v_bfrev_b32_e32 v140, 1
	v_writelane_b32 v250, s1, 55
	s_or_b32 s0, s8, 6
	s_ashr_i32 s1, s0, 31
	s_lshl_b64 s[0:1], s[0:1], 11
	v_writelane_b32 v250, s0, 56
	s_mov_b32 s40, 0x800000
	s_waitcnt lgkmcnt(0)
	s_movk_i32 s33, 0x7fff
	v_writelane_b32 v250, s1, 57
	s_or_b32 s0, s8, 7
	s_ashr_i32 s1, s0, 31
	s_lshl_b64 s[0:1], s[0:1], 11
	v_writelane_b32 v250, s0, 58
	s_mov_b32 s37, 0x41a00000
	s_mov_b32 s38, 0x3fb8aa3b
	v_writelane_b32 v250, s1, 59
	s_or_b32 s0, s8, 8
	s_ashr_i32 s1, s0, 31
	s_lshl_b64 s[0:1], s[0:1], 11
	v_writelane_b32 v250, s0, 60
	s_mov_b32 s42, 0xc2ce8ed0
	s_mov_b32 s43, 0x42b17218
	v_writelane_b32 v250, s1, 61
	s_or_b32 s0, s8, 9
	s_ashr_i32 s1, s0, 31
	s_lshl_b64 s[0:1], s[0:1], 11
	v_writelane_b32 v250, s0, 62
	s_mov_b32 s36, 0xbfb8aa3b
	s_mov_b32 s41, 0x42ce8ed0
	v_writelane_b32 v250, s1, 63
	s_or_b32 s0, s8, 10
	s_ashr_i32 s1, s0, 31
	s_lshl_b64 s[0:1], s[0:1], 11
	v_writelane_b32 v251, s0, 0
	s_mov_b32 s19, 0x10100
	s_mov_b32 s15, 0
	v_writelane_b32 v251, s1, 1
	s_or_b32 s0, s8, 11
	s_ashr_i32 s1, s0, 31
	s_lshl_b64 s[0:1], s[0:1], 11
	v_writelane_b32 v251, s0, 2
	s_mov_b64 s[22:23], 0x1000
	s_mov_b32 s68, 0x3d000000
	v_writelane_b32 v251, s1, 3
	s_or_b32 s0, s8, 12
	s_ashr_i32 s1, s0, 31
	s_lshl_b64 s[0:1], s[0:1], 11
	v_writelane_b32 v251, s0, 4
	s_nop 1
	v_writelane_b32 v251, s1, 5
	s_or_b32 s0, s8, 13
	s_ashr_i32 s1, s0, 31
	s_lshl_b64 s[0:1], s[0:1], 11
	v_writelane_b32 v251, s0, 6
	s_nop 1
	v_writelane_b32 v251, s1, 7
	s_or_b32 s0, s8, 14
	s_ashr_i32 s1, s0, 31
	s_lshl_b64 s[0:1], s[0:1], 11
	v_writelane_b32 v251, s0, 8
	s_nop 1
	v_writelane_b32 v251, s1, 9
	s_or_b32 s0, s8, 15
	s_ashr_i32 s1, s0, 31
	s_lshl_b64 s[0:1], s[0:1], 11
	v_writelane_b32 v251, s0, 10
	s_nop 1
	v_writelane_b32 v251, s1, 11
	s_ashr_i32 s0, s28, 1
	s_cmp_gt_i32 s0, -1
	s_cselect_b64 s[2:3], -1, 0
	v_writelane_b32 v251, s2, 12
	s_cmp_gt_i32 s0, 0
	s_nop 0
	v_writelane_b32 v251, s3, 13
	s_cselect_b64 s[2:3], -1, 0
	v_writelane_b32 v251, s2, 14
	s_cmp_gt_i32 s0, 1
	s_nop 0
	v_writelane_b32 v251, s3, 15
	s_cselect_b64 s[2:3], -1, 0
	v_writelane_b32 v251, s2, 16
	s_cmp_gt_i32 s0, 2
	s_cselect_b64 s[0:1], -1, 0
	v_writelane_b32 v251, s3, 17
	v_writelane_b32 v251, s0, 18
	s_lshl_b32 s6, s28, 3
	s_nop 0
	v_writelane_b32 v251, s1, 19
	s_add_i32 s0, s6, -3
	v_writelane_b32 v251, s0, 20
	s_cmp_eq_u32 s28, 0
	s_mul_i32 s0, s28, 0x240
	s_cselect_b64 s[30:31], -1, 0
	v_writelane_b32 v251, s0, 21
	s_lshl_b32 s0, s28, 13
	v_writelane_b32 v251, s0, 22
	s_or_b32 s0, s6, 1
	s_mul_i32 s7, s0, 0x48
	s_lshl_b32 s1, s0, 10
	v_writelane_b32 v251, s1, 23
	s_or_b32 s1, s6, 2
	s_add_i32 s2, s7, 0x48
	v_writelane_b32 v251, s2, 24
	s_lshl_b32 s2, s1, 10
	v_writelane_b32 v251, s2, 25
	s_or_b32 s2, s6, 3
	s_add_i32 s3, s7, 0x90
	v_writelane_b32 v251, s3, 26
	s_lshl_b32 s3, s2, 10
	v_writelane_b32 v251, s3, 27
	s_or_b32 s3, s6, 4
	s_add_i32 s4, s7, 0xd8
	v_writelane_b32 v251, s4, 28
	s_lshl_b32 s4, s3, 10
	v_writelane_b32 v251, s4, 29
	s_or_b32 s4, s6, 5
	s_add_i32 s5, s7, 0x120
	v_writelane_b32 v251, s5, 30
	s_lshl_b32 s5, s4, 10
	v_writelane_b32 v251, s5, 31
	s_or_b32 s5, s6, 6
	s_add_i32 s10, s7, 0x168
	v_writelane_b32 v251, s10, 32
	s_lshl_b32 s10, s5, 10
	v_writelane_b32 v251, s10, 33
	v_writelane_b32 v251, s6, 34
	s_or_b32 s6, s6, 7
	v_writelane_b32 v251, s7, 35
	s_addk_i32 s7, 0x1b0
	v_writelane_b32 v251, s7, 36
	s_lshl_b32 s7, s6, 10
	s_cmp_lt_u32 s28, 4
	v_writelane_b32 v251, s7, 37
	s_cselect_b64 s[10:11], -1, 0
	v_writelane_b32 v251, s10, 38
	s_cmp_gt_u32 s28, 3
	s_mul_i32 s0, s0, -6
	v_writelane_b32 v251, s11, 39
	s_cselect_b64 s[10:11], -1, 0
	v_writelane_b32 v251, s8, 40
	s_and_b32 s7, s8, 48
	s_cmp_lt_i32 s28, 4
	v_writelane_b32 v251, s9, 41
	v_writelane_b32 v251, s7, 42
	s_cselect_b64 s[8:9], -1, 0
	v_writelane_b32 v251, s8, 43
	s_cmp_gt_i32 s28, 3
	v_writelane_b32 v250, s10, 20
	v_writelane_b32 v251, s9, 44
	s_cselect_b64 s[8:9], -1, 0
	v_writelane_b32 v251, s8, 45
	s_lshl_b32 s7, s28, 5
	s_ashr_i32 s29, s28, 31
	v_writelane_b32 v251, s9, 46
	v_writelane_b32 v251, s7, 47
	s_and_b32 s7, s7, 0x60
	v_writelane_b32 v251, s7, 48
	s_lshl_b32 s7, s28, 1
	v_writelane_b32 v251, s7, 49
	s_lshl_b32 s7, s28, 14
	s_add_i32 s7, s7, 0
	v_writelane_b32 v251, s7, 50
	v_writelane_b32 v251, s0, 51
	s_mul_i32 s0, s1, -6
	v_writelane_b32 v251, s0, 52
	s_mul_i32 s0, s2, -6
	v_writelane_b32 v251, s0, 53
	s_mul_i32 s0, s3, -6
	v_writelane_b32 v251, s0, 54
	s_mul_i32 s0, s4, -6
	v_writelane_b32 v251, s0, 55
	s_mul_i32 s0, s5, -6
	v_writelane_b32 v251, s0, 56
	s_mul_i32 s0, s6, -6
	v_writelane_b32 v251, s0, 57
	s_and_b32 s0, s28, 3
	s_mul_i32 s1, s0, 0x880
	s_add_i32 s2, s1, 0x180
	v_writelane_b32 v251, s2, 58
	s_add_i32 s2, s1, 0x100
	v_writelane_b32 v251, s2, 59
	s_addk_i32 s1, 0x80
	v_writelane_b32 v251, s1, 60
	s_lshl_b32 s0, s0, 12
	v_writelane_b32 v251, s0, 61
	s_lshl_b32 s0, s28, 10
	s_addk_i32 s0, 0xf000
	v_writelane_b32 v251, s0, 62
	s_add_i32 s0, 0, 0x9000
	v_writelane_b32 v251, s0, 63
	s_add_i32 s0, 0, 0x12000
	v_writelane_b32 v252, s0, 0
	s_add_i32 s0, 0, 0x22800
	v_writelane_b32 v252, s0, 1
	s_add_i32 s0, 0, 0x4800
	v_writelane_b32 v252, s0, 2
	s_add_i32 s0, 0, 0x19000
	v_writelane_b32 v252, s0, 3
	s_add_i32 s0, 0, 0x1d000
	v_writelane_b32 v252, s0, 4
	s_add_i32 s0, 0, 0x22000
	v_writelane_b32 v252, s0, 5
	s_lshl_b64 s[0:1], s[28:29], 11
	v_writelane_b32 v252, s0, 6
	v_writelane_b32 v250, s11, 21
	s_add_i32 s34, 0, 0x27f40
	v_writelane_b32 v252, s1, 7
	v_writelane_b32 v252, s26, 8
	v_writelane_b32 v252, s30, 9
	s_mov_b32 s0, s28
	v_writelane_b32 v250, s0, 12
	v_writelane_b32 v252, s31, 10
	v_writelane_b32 v252, s27, 11
	v_mov_b32_e32 v136, s34
	s_mov_b32 s29, 0xc2b17218
	v_writelane_b32 v250, s1, 13
	v_writelane_b32 v252, s34, 12
	s_branch .LBB0_2558

; #define LAS __attribute__((address_space(3)))
;     template <class T> __device__ __forceinline__ T* w(size_t off) const { return (T*)(pp->ws + off); }
; __device__ __forceinline__ float wave_sum(float v) { v = row16_sum(v); return (rlf(v, 0) + rlf(v, 16)) + (rlf(v, 32) + rlf(v, 48)); }
; template <class T> __device__ __forceinline__ LAS T* opq(LAS T* p) { asm volatile("" : "+v"(p)); return p; }
; __device__ __forceinline__ void mixA_unit(const Ctx& c, int l, int a) {
;     const int b = a >> 7, chunk = (a >> 3) & 15, hh = a & 7, r0 = b * 2048 + chunk * 128;
;     LAS unsigned char* WmB = opq(c.lds);
;     LAS unsigned char* vT = opq(c.lds + 36864);
;     LAS float* mixed = opq((LAS float*)(c.lds + 73728));
;     LAS float* st_mean = opq((LAS float*)(c.lds + 73728 + 67584));
;     LAS float* st_rstd = st_mean + 128;
;     const bf16* VA = c.w<bf16>(WS_VA) + (size_t)r0 * 1024; const bf16* UA = c.w<bf16>(WS_UA) + (size_t)r0 * 1024; const bf16* ZA = c.w<bf16>(WS_ZA) + (size_t)r0 * 1024;
;     const int lane = c.lane, wave = c.wave, m = lane & 15, quad = lane >> 4;
; #pragma unroll
;     for (int half = 0; half < 2; ++half) {
;         u32x4 raw[8][2];
; #pragma unroll
;         for (int i = 0; i < 8; ++i) { const bf16* row = VA + (size_t)(wave * 16 + half * 8 + i) * 1024; raw[i][0] = *(const u32x4*)(row + lane * 8); raw[i][1] = *(const u32x4*)(row + 512 + lane * 8); }
; #pragma unroll
;         for (int i = 0; i < 8; ++i) {
;             float x[8], y[8]; unpack8(raw[i][0], x); unpack8(raw[i][1], y);
;             float sm = 0.f, sq = 0.f;
; #pragma unroll
;             for (int e = 0; e < 8; ++e) { sm += x[e] + y[e]; sq += x[e] * x[e] + y[e] * y[e]; }
;             sm = wave_sum(sm); sq = wave_sum(sq);
; __device__ __forceinline__ void phase_M1(Ctx& c, int l, int q, const XcdBarrier& bar) {
;     ...
;         const int u = next_unit(c, q);
;         if (u >= M1_TOTAL) break;
.LBB0_2562:
	s_or_b64 exec, exec, s[0:1]
	s_waitcnt lgkmcnt(0)
	s_barrier
	ds_read_b32 v0, v136
	s_mov_b64 s[0:1], -1
	s_waitcnt lgkmcnt(0)
	v_readfirstlane_b32 s18, v0
	v_readlane_b32 s44, v255, 62
	s_nop 3
	s_mul_i32 s45, s44, 0x590
	s_add_i32 s18, s18, s45
	s_lshl_b32 s45, s44, 9
	s_addk_i32 s45, 0x58f
	s_cmp_gt_i32 s18, s45
	s_cbranch_scc1 .LBB0_2557
	s_cmp_gt_i32 s18, 15
	s_cbranch_scc0 .LBB0_2647
	s_cmpk_gt_u32 s18, 0x10f
	s_cbranch_scc0 .LBB0_2626
	s_cmpk_gt_u32 s18, 0x18f
	s_cbranch_scc0 .LBB0_2613
	s_cmpk_gt_u32 s18, 0x58f
	s_cbranch_scc0 .LBB0_2609
	s_lshl_b32 s0, s18, 4
	s_addk_i32 s0, 0x700
	s_and_b32 s10, s0, 0x1f80
	v_readlane_b32 s0, v251, 63
	v_mov_b32_e32 v60, v17
	v_lshlrev_b32_e32 v58, 3, v66
	v_mov_b32_e32 v63, s0
	v_readlane_b32 s0, v252, 0
	v_ashrrev_i32_e32 v59, 31, v58
	v_lshlrev_b64 v[68:69], 1, v[58:59]
	v_mov_b32_e32 v61, s0
	v_readlane_b32 s0, v252, 1
	v_readlane_b32 s2, v251, 40
	v_cmp_eq_u32_e32 vcc, 0, v66
	v_mov_b32_e32 v65, s0
	s_load_dwordx2 s[4:5], s[90:91], 0xc0
	s_lshl_b32 s0, s10, 11
	v_readlane_b32 s3, v251, 41
	s_waitcnt lgkmcnt(0)
	s_add_u32 s0, s4, s0
	s_addc_u32 s1, s5, 0
	s_add_u32 s6, s0, 0x24700000
	s_addc_u32 s7, s1, 0
	v_readlane_b32 s0, v250, 44
	v_readlane_b32 s1, v250, 45
	s_add_u32 s0, s6, s0
	s_addc_u32 s1, s7, s1
	v_lshl_add_u64 v[0:1], s[0:1], 0, v[68:69]
	global_load_dwordx4 v[70:73], v[0:1], off
	global_load_dwordx4 v[74:77], v[0:1], off offset:1024
	v_readlane_b32 s0, v250, 46
	v_readlane_b32 s1, v250, 47
	s_add_u32 s0, s6, s0
	s_addc_u32 s1, s7, s1
	v_lshl_add_u64 v[0:1], s[0:1], 0, v[68:69]
	v_readlane_b32 s0, v250, 48
	v_readlane_b32 s1, v250, 49
	s_add_u32 s0, s6, s0
	s_addc_u32 s1, s7, s1
	global_load_dwordx4 v[54:57], v[0:1], off
	global_load_dwordx4 v[50:53], v[0:1], off offset:1024
	v_lshl_add_u64 v[0:1], s[0:1], 0, v[68:69]
	v_readlane_b32 s0, v250, 50
	v_readlane_b32 s1, v250, 51
	s_add_u32 s0, s6, s0
	s_addc_u32 s1, s7, s1
	global_load_dwordx4 v[46:49], v[0:1], off
	global_load_dwordx4 v[42:45], v[0:1], off offset:1024
	v_lshl_add_u64 v[0:1], s[0:1], 0, v[68:69]
	v_readlane_b32 s0, v250, 52
	v_readlane_b32 s1, v250, 53
	s_add_u32 s0, s6, s0
	s_addc_u32 s1, s7, s1
	global_load_dwordx4 v[38:41], v[0:1], off
	global_load_dwordx4 v[34:37], v[0:1], off offset:1024
	v_lshl_add_u64 v[0:1], s[0:1], 0, v[68:69]
	v_readlane_b32 s0, v250, 54
	v_readlane_b32 s1, v250, 55
	s_add_u32 s0, s6, s0
	s_addc_u32 s1, s7, s1
	global_load_dwordx4 v[30:33], v[0:1], off
	global_load_dwordx4 v[26:29], v[0:1], off offset:1024
	v_lshl_add_u64 v[0:1], s[0:1], 0, v[68:69]
	v_readlane_b32 s0, v250, 56
	v_readlane_b32 s1, v250, 57
	s_add_u32 s0, s6, s0
	s_addc_u32 s1, s7, s1
	global_load_dwordx4 v[22:25], v[0:1], off
	global_load_dwordx4 v[18:21], v[0:1], off offset:1024
	v_lshl_add_u64 v[0:1], s[0:1], 0, v[68:69]
	v_readlane_b32 s0, v250, 58
	v_readlane_b32 s1, v250, 59
	s_add_u32 s0, s6, s0
	s_addc_u32 s1, s7, s1
	global_load_dwordx4 v[12:15], v[0:1], off
	global_load_dwordx4 v[8:11], v[0:1], off offset:1024
	v_lshl_add_u64 v[0:1], s[0:1], 0, v[68:69]
	global_load_dwordx4 v[4:7], v[0:1], off
	s_nop 0
	global_load_dwordx4 v[0:3], v[0:1], off offset:1024
	s_waitcnt vmcnt(15)
	v_lshlrev_b32_e32 v16, 16, v70
	s_waitcnt vmcnt(14)
	v_lshlrev_b32_e32 v79, 16, v74
	v_and_b32_e32 v59, 0xffff0000, v70
	v_and_b32_e32 v74, 0xffff0000, v74
	v_add_f32_e32 v83, v16, v79
	v_mul_f32_e32 v79, v79, v79
	v_fmac_f32_e32 v79, v16, v16
	v_add_f32_e32 v16, v59, v74
	v_mul_f32_e32 v74, v74, v74
	v_lshlrev_b32_e32 v67, 16, v71
	v_lshlrev_b32_e32 v80, 16, v75
	v_add_f32_e32 v83, 0, v83
	v_fmac_f32_e32 v74, v59, v59
	v_add_f32_e32 v16, v16, v83
	v_add_f32_e32 v59, v79, v74
	v_add_f32_e32 v74, v67, v80
	v_and_b32_e32 v70, 0xffff0000, v71
	v_and_b32_e32 v75, 0xffff0000, v75
	v_add_f32_e32 v16, v74, v16
	v_mul_f32_e32 v74, v80, v80
	v_fmac_f32_e32 v74, v67, v67
	v_add_f32_e32 v67, v70, v75
	v_add_f32_e32 v16, v67, v16
	v_mul_f32_e32 v67, v75, v75
	v_lshlrev_b32_e32 v71, 16, v72
	v_lshlrev_b32_e32 v81, 16, v76
	v_add_f32_e32 v59, v74, v59
	v_fmac_f32_e32 v67, v70, v70
	v_add_f32_e32 v59, v67, v59
	v_add_f32_e32 v67, v71, v81
	v_add_f32_e32 v16, v67, v16
	v_mul_f32_e32 v67, v81, v81
	v_and_b32_e32 v72, 0xffff0000, v72
	v_and_b32_e32 v76, 0xffff0000, v76
	v_fmac_f32_e32 v67, v71, v71
	v_add_f32_e32 v59, v67, v59
	v_add_f32_e32 v67, v72, v76
	v_add_f32_e32 v16, v67, v16
	v_mul_f32_e32 v67, v76, v76
	v_lshlrev_b32_e32 v78, 16, v73
	v_lshlrev_b32_e32 v82, 16, v77
	v_fmac_f32_e32 v67, v72, v72
	v_add_f32_e32 v59, v67, v59
	v_add_f32_e32 v67, v78, v82
	v_add_f32_e32 v16, v67, v16
	v_mul_f32_e32 v67, v82, v82
	v_and_b32_e32 v73, 0xffff0000, v73
	v_and_b32_e32 v77, 0xffff0000, v77
	v_fmac_f32_e32 v67, v78, v78
	v_add_f32_e32 v59, v67, v59
	v_add_f32_e32 v67, v73, v77
	v_add_f32_e32 v16, v67, v16
	v_mul_f32_e32 v67, v77, v77
	v_fmac_f32_e32 v67, v73, v73
	v_add_f32_dpp v16, v16, v16 quad_perm:[1,0,3,2] row_mask:0xf bank_mask:0xf bound_ctrl:1
	v_add_f32_e32 v59, v67, v59
	s_nop 0
	v_add_f32_dpp v16, v16, v16 quad_perm:[2,3,0,1] row_mask:0xf bank_mask:0xf bound_ctrl:1
	s_nop 1
	v_add_f32_dpp v16, v16, v16 row_half_mirror row_mask:0xf bank_mask:0xf bound_ctrl:1
	s_nop 1
	v_add_f32_dpp v16, v16, v16 row_mirror row_mask:0xf bank_mask:0xf bound_ctrl:1
	s_nop 0
	v_readlane_b32 s9, v16, 0
	v_readlane_b32 s12, v16, 16
	v_readlane_b32 s1, v16, 32
	v_readlane_b32 s11, v16, 48
	v_add_f32_dpp v16, v59, v59 quad_perm:[1,0,3,2] row_mask:0xf bank_mask:0xf bound_ctrl:1
	s_nop 1
	v_add_f32_dpp v16, v16, v16 quad_perm:[2,3,0,1] row_mask:0xf bank_mask:0xf bound_ctrl:1
	s_nop 1
	v_add_f32_dpp v16, v16, v16 row_half_mirror row_mask:0xf bank_mask:0xf bound_ctrl:1
	s_nop 1
	v_add_f32_dpp v16, v16, v16 row_mirror row_mask:0xf bank_mask:0xf bound_ctrl:1
	s_nop 0
	v_readlane_b32 s8, v16, 0
	v_readlane_b32 s14, v16, 16
	v_readlane_b32 s0, v16, 32
	v_readlane_b32 s13, v16, 48
	v_lshl_add_u32 v16, s2, 2, v65
	s_and_saveexec_b64 s[2:3], vcc
	s_cbranch_execz .LBB0_2569
	v_mov_b32_e32 v70, s14
	v_mov_b32_e32 v71, s12
	v_mov_b32_e32 v72, s13
	v_mov_b32_e32 v73, s11
	v_pk_add_f32 v[70:71], s[8:9], v[70:71]
	v_pk_add_f32 v[72:73], s[0:1], v[72:73]
	s_mov_b32 s0, 0x3a800000
	v_pk_add_f32 v[70:71], v[70:71], v[72:73]
	s_nop 0
	v_pk_mul_f32 v[70:71], v[70:71], s[0:1] op_sel_hi:[1,0]
	s_nop 0
	v_fma_f32 v59, -v71, v71, v70
	v_max_f32_e32 v59, 0, v59
	v_add_f32_e32 v59, 0x358637bd, v59
	v_mul_f32_e32 v67, 0x4b800000, v59
	v_cmp_gt_f32_e64 s[0:1], s40, v59
	s_nop 1
	v_cndmask_b32_e64 v59, v59, v67, s[0:1]
	v_rsq_f32_e32 v59, v59
	s_nop 0
	v_mul_f32_e32 v67, 0x45800000, v59
	v_cndmask_b32_e64 v59, v59, v67, s[0:1]
	ds_write2st64_b32 v16, v71, v59 offset1:2

; __device__ __forceinline__ void phase_M1(Ctx& c, int l, int q, const XcdBarrier& bar) {
;     for (;;) {
;         const int u = next_unit(c, q);
;         if (u >= M1_TOTAL) break;
;         m1_dispatch(c, l, u);
.Lmx_tramp:
	s_branch .LBB0_2552

.LBB0_2861:
	v_readlane_b32 s2, v255, 62
	s_nop 3
	s_cmp_eq_u32 s2, 0
	s_cbranch_scc1 .Lmx_m2go
	s_mov_b32 s58, s28
	s_branch .LBB0_3049

; __device__ __forceinline__ void phase_M1(Ctx& c, int l, int q, const XcdBarrier& bar) {
;     for (;;) {
;         const int u = next_unit(c, q);
;         if (u >= M1_TOTAL) break;
;         m1_dispatch(c, l, u);
; __device__ __forceinline__ void phase_M2(Ctx& c, int l, int q, const XcdBarrier& bar) {
;     if ((int)blockIdx.x < M2_NDP) dscan_unit<0>(c, l, (int)blockIdx.x >> 4, (int)blockIdx.x & 15);
;     for (;;) {
;         const int u = next_unit(c, q);
;         const int pskip = ((int)gridDim.x == 256) ? PRO_NMOD : 0;
;         if (u >= M2_TOTAL + (l == 0 ? PRO_N - pskip : 0)) break;
;         if (u < M2_TOTAL) m2_dispatch(c, l, u); else prologue_unit(c, 1, pskip + u - M2_TOTAL);
;     }
.LBB0_2998:
	v_readlane_b32 s2, v255, 62
	s_nop 3
	s_cmp_eq_u32 s2, 0
	s_cbranch_scc0 .Lmx_m2exit
	v_writelane_b32 v255, 1, 62
	v_readlane_b32 s39, v250, 7
	s_mov_b32 s28, s80
	s_mov_b64 s[0:1], -1
	s_branch .Lmx_tramp
